# latent RWKV step loop: row-B broadcast via op_sel (no v_mov copies) and body unrolled x2 with LDS immediates shifted (4 steps per back edge), on v27
# speedup vs baseline: 1.0627x; 1.0008x over previous
.LBB0_493:
	v_add_u32_e32 v137, s14, v197
	v_add_u32_e32 v136, s14, v148
	v_pk_mul_f32 v[134:135], v[104:105], v[36:37]
	v_pk_mul_f32 v[104:105], v[104:105], v[40:41]
	v_pk_fma_f32 v[134:135], v[38:39], v[106:107], v[134:135]
	v_pk_fma_f32 v[104:105], v[42:43], v[106:107], v[104:105]
	v_pk_fma_f32 v[134:135], v[32:33], v[112:113], v[134:135]
	v_pk_fma_f32 v[104:105], v[44:45], v[112:113], v[104:105]
	v_pk_fma_f32 v[134:135], v[34:35], v[114:115], v[134:135]
	v_pk_fma_f32 v[138:139], v[46:47], v[114:115], v[104:105]
	ds_read_b128 v[104:107], v137 offset:33024
	ds_read_b128 v[112:115], v137 offset:33040
	v_add_f32_e32 v134, v134, v135
	v_add_f32_e32 v135, v138, v139
	v_pk_mul_f32 v[140:141], v[88:89], v[130:131] op_sel_hi:[1,0]
	v_add_f32_dpp v134, v134, v134 quad_perm:[1,0,3,2] row_mask:0xf bank_mask:0xf bound_ctrl:1
	v_add_f32_dpp v135, v135, v135 quad_perm:[1,0,3,2] row_mask:0xf bank_mask:0xf bound_ctrl:1
	v_pk_mul_f32 v[142:143], v[90:91], v[130:131] op_sel_hi:[1,0]
	v_add_f32_dpp v134, v134, v134 quad_perm:[2,3,0,1] row_mask:0xf bank_mask:0xf bound_ctrl:1
	v_add_f32_dpp v135, v135, v135 quad_perm:[2,3,0,1] row_mask:0xf bank_mask:0xf bound_ctrl:1
	v_pk_mul_f32 v[144:145], v[96:97], v[130:131] op_sel_hi:[1,0]
	v_pk_mul_f32 v[146:147], v[98:99], v[130:131] op_sel_hi:[1,0]
	v_pk_mul_f32 v[160:161], v[88:89], v[130:131] op_sel:[0,1] op_sel_hi:[1,1]
	v_add_f32_dpp v134, v134, v134 row_half_mirror row_mask:0xf bank_mask:0xf bound_ctrl:1
	v_add_f32_dpp v138, v135, v135 row_half_mirror row_mask:0xf bank_mask:0xf bound_ctrl:1
	v_pk_mul_f32 v[162:163], v[90:91], v[130:131] op_sel:[0,1] op_sel_hi:[1,1]
	v_pk_mul_f32 v[164:165], v[96:97], v[130:131] op_sel:[0,1] op_sel_hi:[1,1]
	v_pk_mul_f32 v[132:133], v[98:99], v[130:131] op_sel:[0,1] op_sel_hi:[1,1]
	ds_read_b128 v[96:99], v137 offset:8448
	ds_read_b128 v[88:91], v137 offset:8464
	ds_read2_b32 v[130:131], v136 offset1:32
	s_waitcnt lgkmcnt(11)
	v_pk_fma_f32 v[140:141], v[134:135], v[92:93], v[140:141] op_sel_hi:[0,1,1]
	v_pk_fma_f32 v[142:143], v[134:135], v[94:95], v[142:143] op_sel_hi:[0,1,1]
	v_pk_fma_f32 v[144:145], v[134:135], v[100:101], v[144:145] op_sel_hi:[0,1,1]
	v_pk_fma_f32 v[134:135], v[134:135], v[102:103], v[146:147] op_sel_hi:[0,1,1]
	v_pk_fma_f32 v[146:147], v[138:139], v[92:93], v[160:161] op_sel_hi:[0,1,1]
	v_pk_fma_f32 v[160:161], v[138:139], v[94:95], v[162:163] op_sel_hi:[0,1,1]
	v_pk_fma_f32 v[132:133], v[138:139], v[102:103], v[132:133] op_sel_hi:[0,1,1]
	s_waitcnt lgkmcnt(10)
	v_pk_fma_f32 v[36:37], v[36:37], v[108:109], v[140:141]
	v_pk_fma_f32 v[108:109], v[40:41], v[108:109], v[146:147]
	v_pk_fma_f32 v[162:163], v[138:139], v[100:101], v[164:165] op_sel_hi:[0,1,1]
	ds_read_b128 v[100:103], v137 offset:41216
	ds_read_b128 v[92:95], v137 offset:41232
	v_pk_fma_f32 v[38:39], v[38:39], v[110:111], v[142:143]
	s_waitcnt lgkmcnt(10)
	v_pk_fma_f32 v[34:35], v[34:35], v[118:119], v[134:135]
	v_pk_fma_f32 v[110:111], v[42:43], v[110:111], v[160:161]
	v_pk_fma_f32 v[118:119], v[46:47], v[118:119], v[132:133]
	v_pk_mul_f32 v[132:133], v[120:121], v[36:37]
	v_pk_mul_f32 v[120:121], v[120:121], v[108:109]
	v_pk_fma_f32 v[32:33], v[32:33], v[116:117], v[144:145]
	v_pk_fma_f32 v[116:117], v[44:45], v[116:117], v[162:163]
	v_pk_fma_f32 v[132:133], v[38:39], v[122:123], v[132:133]
	v_pk_fma_f32 v[120:121], v[110:111], v[122:123], v[120:121]
	s_waitcnt lgkmcnt(9)
	v_pk_fma_f32 v[132:133], v[32:33], v[124:125], v[132:133]
	v_pk_fma_f32 v[120:121], v[116:117], v[124:125], v[120:121]
	v_pk_fma_f32 v[132:133], v[34:35], v[126:127], v[132:133]
	v_pk_fma_f32 v[134:135], v[118:119], v[126:127], v[120:121]
	v_add_f32_e32 v132, v132, v133
	v_add_f32_e32 v133, v134, v135
	ds_read_b128 v[40:43], v137 offset:24832
	v_add_f32_dpp v132, v132, v132 quad_perm:[1,0,3,2] row_mask:0xf bank_mask:0xf bound_ctrl:1
	v_add_f32_dpp v133, v133, v133 quad_perm:[1,0,3,2] row_mask:0xf bank_mask:0xf bound_ctrl:1
	ds_read_b128 v[44:47], v137 offset:24848
	v_add_f32_dpp v132, v132, v132 quad_perm:[2,3,0,1] row_mask:0xf bank_mask:0xf bound_ctrl:1
	v_add_f32_dpp v133, v133, v133 quad_perm:[2,3,0,1] row_mask:0xf bank_mask:0xf bound_ctrl:1
	ds_read_b128 v[124:127], v137 offset:256
	v_add_f32_dpp v132, v132, v132 row_half_mirror row_mask:0xf bank_mask:0xf bound_ctrl:1
	v_add_f32_dpp v133, v133, v133 row_half_mirror row_mask:0xf bank_mask:0xf bound_ctrl:1
	ds_read_b128 v[120:123], v137 offset:272
	ds_write_b32 v136, v132 offset:32512
	ds_write_b32 v136, v133 offset:32640
	s_waitcnt lgkmcnt(11)
	v_pk_mul_f32 v[132:133], v[104:105], v[36:37]
	v_pk_mul_f32 v[104:105], v[104:105], v[108:109]
	v_pk_fma_f32 v[132:133], v[38:39], v[106:107], v[132:133]
	v_pk_fma_f32 v[104:105], v[110:111], v[106:107], v[104:105]
	v_pk_fma_f32 v[132:133], v[32:33], v[112:113], v[132:133]
	v_pk_fma_f32 v[104:105], v[116:117], v[112:113], v[104:105]
	v_pk_fma_f32 v[132:133], v[34:35], v[114:115], v[132:133]
	v_pk_fma_f32 v[134:135], v[118:119], v[114:115], v[104:105]
	ds_read_b128 v[104:107], v137 offset:33280
	ds_read_b128 v[112:115], v137 offset:33296
	v_add_f32_e32 v132, v132, v133
	v_add_f32_e32 v133, v134, v135
	s_waitcnt lgkmcnt(10)
	v_pk_mul_f32 v[138:139], v[96:97], v[130:131] op_sel_hi:[1,0]
	v_add_f32_dpp v132, v132, v132 quad_perm:[1,0,3,2] row_mask:0xf bank_mask:0xf bound_ctrl:1
	v_add_f32_dpp v133, v133, v133 quad_perm:[1,0,3,2] row_mask:0xf bank_mask:0xf bound_ctrl:1
	v_pk_mul_f32 v[140:141], v[98:99], v[130:131] op_sel_hi:[1,0]
	v_pk_mul_f32 v[142:143], v[88:89], v[130:131] op_sel_hi:[1,0]
	v_pk_mul_f32 v[144:145], v[90:91], v[130:131] op_sel_hi:[1,0]
	v_add_f32_dpp v132, v132, v132 quad_perm:[2,3,0,1] row_mask:0xf bank_mask:0xf bound_ctrl:1
	v_add_f32_dpp v133, v133, v133 quad_perm:[2,3,0,1] row_mask:0xf bank_mask:0xf bound_ctrl:1
	v_pk_mul_f32 v[146:147], v[96:97], v[130:131] op_sel:[0,1] op_sel_hi:[1,1]
	v_add_f32_dpp v132, v132, v132 row_half_mirror row_mask:0xf bank_mask:0xf bound_ctrl:1
	v_add_f32_dpp v134, v133, v133 row_half_mirror row_mask:0xf bank_mask:0xf bound_ctrl:1
	v_pk_mul_f32 v[160:161], v[98:99], v[130:131] op_sel:[0,1] op_sel_hi:[1,1]
	s_waitcnt lgkmcnt(8)
	v_pk_fma_f32 v[138:139], v[132:133], v[100:101], v[138:139] op_sel_hi:[0,1,1]
	v_pk_fma_f32 v[140:141], v[132:133], v[102:103], v[140:141] op_sel_hi:[0,1,1]
	v_pk_fma_f32 v[142:143], v[132:133], v[92:93], v[142:143] op_sel_hi:[0,1,1]
	v_pk_fma_f32 v[132:133], v[132:133], v[94:95], v[144:145] op_sel_hi:[0,1,1]
	v_pk_fma_f32 v[144:145], v[134:135], v[100:101], v[146:147] op_sel_hi:[0,1,1]
	v_pk_mul_f32 v[162:163], v[88:89], v[130:131] op_sel:[0,1] op_sel_hi:[1,1]
	v_pk_fma_f32 v[146:147], v[134:135], v[102:103], v[160:161] op_sel_hi:[0,1,1]
	s_waitcnt lgkmcnt(7)
	v_pk_fma_f32 v[36:37], v[36:37], v[40:41], v[138:139]
	v_pk_fma_f32 v[40:41], v[108:109], v[40:41], v[144:145]
	v_pk_mul_f32 v[164:165], v[90:91], v[130:131] op_sel:[0,1] op_sel_hi:[1,1]
	ds_read_b128 v[88:91], v137 offset:8704
	ds_read_b128 v[96:99], v137 offset:8720
	ds_read2_b32 v[130:131], v136 offset0:64 offset1:96
	v_pk_fma_f32 v[160:161], v[134:135], v[92:93], v[162:163] op_sel_hi:[0,1,1]
	v_pk_fma_f32 v[38:39], v[38:39], v[42:43], v[140:141]
	s_waitcnt lgkmcnt(8)
	v_pk_fma_f32 v[34:35], v[34:35], v[46:47], v[132:133]
	v_pk_fma_f32 v[42:43], v[110:111], v[42:43], v[146:147]
	v_pk_mul_f32 v[132:133], v[124:125], v[36:37]
	v_pk_mul_f32 v[124:125], v[124:125], v[40:41]
	v_pk_fma_f32 v[134:135], v[134:135], v[94:95], v[164:165] op_sel_hi:[0,1,1]
	ds_read_b128 v[92:95], v137 offset:41472
	ds_read_b128 v[100:103], v137 offset:41488
	v_pk_fma_f32 v[32:33], v[32:33], v[44:45], v[142:143]
	v_pk_fma_f32 v[44:45], v[116:117], v[44:45], v[160:161]
	v_pk_fma_f32 v[132:133], v[38:39], v[126:127], v[132:133]
	v_pk_fma_f32 v[124:125], v[42:43], v[126:127], v[124:125]
	v_pk_fma_f32 v[46:47], v[118:119], v[46:47], v[134:135]
	s_waitcnt lgkmcnt(9)
	v_pk_fma_f32 v[132:133], v[32:33], v[120:121], v[132:133]
	v_pk_fma_f32 v[120:121], v[44:45], v[120:121], v[124:125]
	v_pk_fma_f32 v[132:133], v[34:35], v[122:123], v[132:133]
	v_pk_fma_f32 v[134:135], v[46:47], v[122:123], v[120:121]
	v_add_f32_e32 v132, v132, v133
	v_add_f32_e32 v133, v134, v135
	ds_read_b128 v[108:111], v137 offset:25088
	v_add_f32_dpp v132, v132, v132 quad_perm:[1,0,3,2] row_mask:0xf bank_mask:0xf bound_ctrl:1
	v_add_f32_dpp v133, v133, v133 quad_perm:[1,0,3,2] row_mask:0xf bank_mask:0xf bound_ctrl:1
	ds_read_b128 v[116:119], v137 offset:25104
	v_add_f32_dpp v132, v132, v132 quad_perm:[2,3,0,1] row_mask:0xf bank_mask:0xf bound_ctrl:1
	v_add_f32_dpp v133, v133, v133 quad_perm:[2,3,0,1] row_mask:0xf bank_mask:0xf bound_ctrl:1
	ds_read_b128 v[120:123], v137 offset:512
	v_add_f32_dpp v132, v132, v132 row_half_mirror row_mask:0xf bank_mask:0xf bound_ctrl:1
	v_add_f32_dpp v133, v133, v133 row_half_mirror row_mask:0xf bank_mask:0xf bound_ctrl:1
	ds_read_b128 v[124:127], v137 offset:528
	ds_write_b32 v136, v132 offset:32768
	ds_write_b32 v136, v133 offset:32896
	s_waitcnt lgkmcnt(8)
	v_pk_mul_f32 v[134:135], v[104:105], v[36:37]
	v_pk_mul_f32 v[104:105], v[104:105], v[40:41]
	v_pk_fma_f32 v[134:135], v[38:39], v[106:107], v[134:135]
	v_pk_fma_f32 v[104:105], v[42:43], v[106:107], v[104:105]
	v_pk_fma_f32 v[134:135], v[32:33], v[112:113], v[134:135]
	v_pk_fma_f32 v[104:105], v[44:45], v[112:113], v[104:105]
	v_pk_fma_f32 v[134:135], v[34:35], v[114:115], v[134:135]
	v_pk_fma_f32 v[138:139], v[46:47], v[114:115], v[104:105]
	ds_read_b128 v[104:107], v137 offset:33536
	ds_read_b128 v[112:115], v137 offset:33552
	v_add_f32_e32 v134, v134, v135
	v_add_f32_e32 v135, v138, v139
	v_pk_mul_f32 v[140:141], v[88:89], v[130:131] op_sel_hi:[1,0]
	v_add_f32_dpp v134, v134, v134 quad_perm:[1,0,3,2] row_mask:0xf bank_mask:0xf bound_ctrl:1
	v_add_f32_dpp v135, v135, v135 quad_perm:[1,0,3,2] row_mask:0xf bank_mask:0xf bound_ctrl:1
	v_pk_mul_f32 v[142:143], v[90:91], v[130:131] op_sel_hi:[1,0]
	v_add_f32_dpp v134, v134, v134 quad_perm:[2,3,0,1] row_mask:0xf bank_mask:0xf bound_ctrl:1
	v_add_f32_dpp v135, v135, v135 quad_perm:[2,3,0,1] row_mask:0xf bank_mask:0xf bound_ctrl:1
	v_pk_mul_f32 v[144:145], v[96:97], v[130:131] op_sel_hi:[1,0]
	v_pk_mul_f32 v[146:147], v[98:99], v[130:131] op_sel_hi:[1,0]
	v_pk_mul_f32 v[160:161], v[88:89], v[130:131] op_sel:[0,1] op_sel_hi:[1,1]
	v_add_f32_dpp v134, v134, v134 row_half_mirror row_mask:0xf bank_mask:0xf bound_ctrl:1
	v_add_f32_dpp v138, v135, v135 row_half_mirror row_mask:0xf bank_mask:0xf bound_ctrl:1
	v_pk_mul_f32 v[162:163], v[90:91], v[130:131] op_sel:[0,1] op_sel_hi:[1,1]
	v_pk_mul_f32 v[164:165], v[96:97], v[130:131] op_sel:[0,1] op_sel_hi:[1,1]
	v_pk_mul_f32 v[132:133], v[98:99], v[130:131] op_sel:[0,1] op_sel_hi:[1,1]
	ds_read_b128 v[96:99], v137 offset:8960
	ds_read_b128 v[88:91], v137 offset:8976
	ds_read2_b32 v[130:131], v136 offset0:128 offset1:160
	s_waitcnt lgkmcnt(11)
	v_pk_fma_f32 v[140:141], v[134:135], v[92:93], v[140:141] op_sel_hi:[0,1,1]
	v_pk_fma_f32 v[142:143], v[134:135], v[94:95], v[142:143] op_sel_hi:[0,1,1]
	v_pk_fma_f32 v[144:145], v[134:135], v[100:101], v[144:145] op_sel_hi:[0,1,1]
	v_pk_fma_f32 v[134:135], v[134:135], v[102:103], v[146:147] op_sel_hi:[0,1,1]
	v_pk_fma_f32 v[146:147], v[138:139], v[92:93], v[160:161] op_sel_hi:[0,1,1]
	v_pk_fma_f32 v[160:161], v[138:139], v[94:95], v[162:163] op_sel_hi:[0,1,1]
	v_pk_fma_f32 v[132:133], v[138:139], v[102:103], v[132:133] op_sel_hi:[0,1,1]
	s_waitcnt lgkmcnt(10)
	v_pk_fma_f32 v[36:37], v[36:37], v[108:109], v[140:141]
	v_pk_fma_f32 v[108:109], v[40:41], v[108:109], v[146:147]
	v_pk_fma_f32 v[162:163], v[138:139], v[100:101], v[164:165] op_sel_hi:[0,1,1]
	ds_read_b128 v[100:103], v137 offset:41728
	ds_read_b128 v[92:95], v137 offset:41744
	v_pk_fma_f32 v[38:39], v[38:39], v[110:111], v[142:143]
	s_waitcnt lgkmcnt(10)
	v_pk_fma_f32 v[34:35], v[34:35], v[118:119], v[134:135]
	v_pk_fma_f32 v[110:111], v[42:43], v[110:111], v[160:161]
	v_pk_fma_f32 v[118:119], v[46:47], v[118:119], v[132:133]
	v_pk_mul_f32 v[132:133], v[120:121], v[36:37]
	v_pk_mul_f32 v[120:121], v[120:121], v[108:109]
	v_pk_fma_f32 v[32:33], v[32:33], v[116:117], v[144:145]
	v_pk_fma_f32 v[116:117], v[44:45], v[116:117], v[162:163]
	v_pk_fma_f32 v[132:133], v[38:39], v[122:123], v[132:133]
	v_pk_fma_f32 v[120:121], v[110:111], v[122:123], v[120:121]
	s_waitcnt lgkmcnt(9)
	v_pk_fma_f32 v[132:133], v[32:33], v[124:125], v[132:133]
	v_pk_fma_f32 v[120:121], v[116:117], v[124:125], v[120:121]
	v_pk_fma_f32 v[132:133], v[34:35], v[126:127], v[132:133]
	v_pk_fma_f32 v[134:135], v[118:119], v[126:127], v[120:121]
	v_add_f32_e32 v132, v132, v133
	v_add_f32_e32 v133, v134, v135
	ds_read_b128 v[40:43], v137 offset:25344
	v_add_f32_dpp v132, v132, v132 quad_perm:[1,0,3,2] row_mask:0xf bank_mask:0xf bound_ctrl:1
	v_add_f32_dpp v133, v133, v133 quad_perm:[1,0,3,2] row_mask:0xf bank_mask:0xf bound_ctrl:1
	ds_read_b128 v[44:47], v137 offset:25360
	v_add_f32_dpp v132, v132, v132 quad_perm:[2,3,0,1] row_mask:0xf bank_mask:0xf bound_ctrl:1
	v_add_f32_dpp v133, v133, v133 quad_perm:[2,3,0,1] row_mask:0xf bank_mask:0xf bound_ctrl:1
	ds_read_b128 v[124:127], v137 offset:768
	v_add_f32_dpp v132, v132, v132 row_half_mirror row_mask:0xf bank_mask:0xf bound_ctrl:1
	v_add_f32_dpp v133, v133, v133 row_half_mirror row_mask:0xf bank_mask:0xf bound_ctrl:1
	ds_read_b128 v[120:123], v137 offset:784
	ds_write_b32 v136, v132 offset:33024
	ds_write_b32 v136, v133 offset:33152
	s_waitcnt lgkmcnt(11)
	v_pk_mul_f32 v[132:133], v[104:105], v[36:37]
	v_pk_mul_f32 v[104:105], v[104:105], v[108:109]
	v_pk_fma_f32 v[132:133], v[38:39], v[106:107], v[132:133]
	v_pk_fma_f32 v[104:105], v[110:111], v[106:107], v[104:105]
	v_pk_fma_f32 v[132:133], v[32:33], v[112:113], v[132:133]
	v_pk_fma_f32 v[104:105], v[116:117], v[112:113], v[104:105]
	v_pk_fma_f32 v[132:133], v[34:35], v[114:115], v[132:133]
	v_pk_fma_f32 v[134:135], v[118:119], v[114:115], v[104:105]
	ds_read_b128 v[104:107], v137 offset:33792
	ds_read_b128 v[112:115], v137 offset:33808
	v_add_f32_e32 v132, v132, v133
	v_add_f32_e32 v133, v134, v135
	s_waitcnt lgkmcnt(10)
	v_pk_mul_f32 v[138:139], v[96:97], v[130:131] op_sel_hi:[1,0]
	v_add_f32_dpp v132, v132, v132 quad_perm:[1,0,3,2] row_mask:0xf bank_mask:0xf bound_ctrl:1
	v_add_f32_dpp v133, v133, v133 quad_perm:[1,0,3,2] row_mask:0xf bank_mask:0xf bound_ctrl:1
	v_pk_mul_f32 v[140:141], v[98:99], v[130:131] op_sel_hi:[1,0]
	v_pk_mul_f32 v[142:143], v[88:89], v[130:131] op_sel_hi:[1,0]
	v_pk_mul_f32 v[144:145], v[90:91], v[130:131] op_sel_hi:[1,0]
	v_add_f32_dpp v132, v132, v132 quad_perm:[2,3,0,1] row_mask:0xf bank_mask:0xf bound_ctrl:1
	v_add_f32_dpp v133, v133, v133 quad_perm:[2,3,0,1] row_mask:0xf bank_mask:0xf bound_ctrl:1
	v_pk_mul_f32 v[146:147], v[96:97], v[130:131] op_sel:[0,1] op_sel_hi:[1,1]
	v_add_f32_dpp v132, v132, v132 row_half_mirror row_mask:0xf bank_mask:0xf bound_ctrl:1
	v_add_f32_dpp v134, v133, v133 row_half_mirror row_mask:0xf bank_mask:0xf bound_ctrl:1
	v_pk_mul_f32 v[160:161], v[98:99], v[130:131] op_sel:[0,1] op_sel_hi:[1,1]
	s_waitcnt lgkmcnt(8)
	v_pk_fma_f32 v[138:139], v[132:133], v[100:101], v[138:139] op_sel_hi:[0,1,1]
	v_pk_fma_f32 v[140:141], v[132:133], v[102:103], v[140:141] op_sel_hi:[0,1,1]
	v_pk_fma_f32 v[142:143], v[132:133], v[92:93], v[142:143] op_sel_hi:[0,1,1]
	v_pk_fma_f32 v[132:133], v[132:133], v[94:95], v[144:145] op_sel_hi:[0,1,1]
	v_pk_fma_f32 v[144:145], v[134:135], v[100:101], v[146:147] op_sel_hi:[0,1,1]
	v_pk_mul_f32 v[162:163], v[88:89], v[130:131] op_sel:[0,1] op_sel_hi:[1,1]
	v_pk_fma_f32 v[146:147], v[134:135], v[102:103], v[160:161] op_sel_hi:[0,1,1]
	s_waitcnt lgkmcnt(7)
	v_pk_fma_f32 v[36:37], v[36:37], v[40:41], v[138:139]
	v_pk_fma_f32 v[40:41], v[108:109], v[40:41], v[144:145]
	v_pk_mul_f32 v[164:165], v[90:91], v[130:131] op_sel:[0,1] op_sel_hi:[1,1]
	ds_read_b128 v[88:91], v137 offset:9216
	ds_read_b128 v[96:99], v137 offset:9232
	ds_read2_b32 v[130:131], v136 offset0:192 offset1:224
	v_pk_fma_f32 v[160:161], v[134:135], v[92:93], v[162:163] op_sel_hi:[0,1,1]
	v_pk_fma_f32 v[38:39], v[38:39], v[42:43], v[140:141]
	s_waitcnt lgkmcnt(8)
	v_pk_fma_f32 v[34:35], v[34:35], v[46:47], v[132:133]
	v_pk_fma_f32 v[42:43], v[110:111], v[42:43], v[146:147]
	v_pk_mul_f32 v[132:133], v[124:125], v[36:37]
	v_pk_mul_f32 v[124:125], v[124:125], v[40:41]
	v_pk_fma_f32 v[134:135], v[134:135], v[94:95], v[164:165] op_sel_hi:[0,1,1]
	ds_read_b128 v[92:95], v137 offset:41984
	ds_read_b128 v[100:103], v137 offset:42000
	v_pk_fma_f32 v[32:33], v[32:33], v[44:45], v[142:143]
	v_pk_fma_f32 v[44:45], v[116:117], v[44:45], v[160:161]
	v_pk_fma_f32 v[132:133], v[38:39], v[126:127], v[132:133]
	v_pk_fma_f32 v[124:125], v[42:43], v[126:127], v[124:125]
	v_pk_fma_f32 v[46:47], v[118:119], v[46:47], v[134:135]
	s_waitcnt lgkmcnt(9)
	v_pk_fma_f32 v[132:133], v[32:33], v[120:121], v[132:133]
	v_pk_fma_f32 v[120:121], v[44:45], v[120:121], v[124:125]
	v_pk_fma_f32 v[132:133], v[34:35], v[122:123], v[132:133]
	v_pk_fma_f32 v[134:135], v[46:47], v[122:123], v[120:121]
	v_add_f32_e32 v132, v132, v133
	v_add_f32_e32 v133, v134, v135
	ds_read_b128 v[108:111], v137 offset:25600
	v_add_f32_dpp v132, v132, v132 quad_perm:[1,0,3,2] row_mask:0xf bank_mask:0xf bound_ctrl:1
	v_add_f32_dpp v133, v133, v133 quad_perm:[1,0,3,2] row_mask:0xf bank_mask:0xf bound_ctrl:1
	ds_read_b128 v[116:119], v137 offset:25616
	v_add_f32_dpp v132, v132, v132 quad_perm:[2,3,0,1] row_mask:0xf bank_mask:0xf bound_ctrl:1
	v_add_f32_dpp v133, v133, v133 quad_perm:[2,3,0,1] row_mask:0xf bank_mask:0xf bound_ctrl:1
	ds_read_b128 v[120:123], v137 offset:1024
	v_add_f32_dpp v132, v132, v132 row_half_mirror row_mask:0xf bank_mask:0xf bound_ctrl:1
	v_add_f32_dpp v133, v133, v133 row_half_mirror row_mask:0xf bank_mask:0xf bound_ctrl:1
	ds_read_b128 v[124:127], v137 offset:1040
	ds_write_b32 v136, v132 offset:33280
	ds_write_b32 v136, v133 offset:33408
	s_waitcnt lgkmcnt(8)
	s_addk_i32 s14, 0x400
	s_cmpk_eq_i32 s14, 0x2000
	s_cbranch_scc0 .LBB0_493
	s_waitcnt lgkmcnt(0)
	s_barrier
	ds_read_b128 v[88:91], v195 offset:49152
	ds_read_b128 v[92:95], v195 offset:49168
	v_mov_b64_e32 v[106:107], v[86:87]
	v_mov_b64_e32 v[98:99], v[74:75]
	v_mov_b64_e32 v[110:111], v[78:79]
	s_waitcnt lgkmcnt(1)
	v_cvt_pk_bf16_f32 v88, v88, v89
	v_cvt_pk_bf16_f32 v89, v90, v91
	s_waitcnt lgkmcnt(0)
	v_cvt_pk_bf16_f32 v90, v92, v93
	v_lshlrev_b64 v[92:93], 10, v[128:129]
	v_cvt_pk_bf16_f32 v91, v94, v95
	v_lshl_add_u64 v[92:93], v[150:151], 0, v[92:93]
	global_store_dwordx4 v[92:93], v[88:91], off
	v_mov_b64_e32 v[114:115], v[82:83]
	s_cmp_eq_u32 s2, 64
	v_mov_b64_e32 v[90:91], v[70:71]
	v_mov_b64_e32 v[104:105], v[84:85]
	v_mov_b64_e32 v[88:89], v[68:69]
	v_mov_b64_e32 v[96:97], v[72:73]
	v_mov_b64_e32 v[108:109], v[76:77]
	v_mov_b64_e32 v[112:113], v[80:81]
	s_mov_b32 s15, s2
	s_cbranch_scc0 .LBB0_481
	s_setprio 0
	v_mov_b32_e32 v158, v222
	v_mov_b32_e32 v159, v223
	s_barrier
	s_branch .LBB0_395
